# barrier release on the arrival counter: every WG polls TOP >= (gen+1)*nx; TOPGEN bump and XGEN relay removed (on keep_v6)
# speedup vs baseline: 1.0293x; 1.0010x over previous
.LBB0_138:
	s_or_b64 exec, exec, s[14:15]
	v_cvt_f32_u32_e32 v5, v3
	s_waitcnt vmcnt(0)
	v_readfirstlane_b32 s9, v4
	v_sub_u32_e32 v4, 0, v3
	v_rcp_iflag_f32_e32 v5, v5
	v_add_u32_e32 v6, s9, v0
	v_mul_f32_e32 v5, 0x4f7ffffe, v5
	v_cvt_u32_f32_e32 v5, v5
	v_mul_lo_u32 v0, v4, v5
	v_mul_hi_u32 v0, v5, v0
	v_add_u32_e32 v0, v5, v0
	v_mul_hi_u32 v0, v6, v0
	v_mul_lo_u32 v4, v0, v3
	v_sub_u32_e32 v4, v6, v4
	v_add_u32_e32 v5, 1, v0
	v_cmp_ge_u32_e32 vcc, v4, v3
	s_nop 1
	v_cndmask_b32_e32 v0, v0, v5, vcc
	v_sub_u32_e32 v5, v4, v3
	v_cndmask_b32_e32 v4, v4, v5, vcc
	v_add_u32_e32 v5, 1, v0
	v_cmp_ge_u32_e32 vcc, v4, v3
	v_add_u32_e32 v4, 1, v6
	s_nop 0
	v_cndmask_b32_e32 v0, v0, v5, vcc
	v_mul_lo_u32 v5, v3, v0
	v_add_u32_e32 v3, v5, v3
	v_cmp_ne_u32_e32 vcc, v4, v3
	s_and_saveexec_b64 s[12:13], vcc
	s_xor_b64 s[12:13], exec, s[12:13]
	s_cbranch_execz .LBB0_152
	s_waitcnt lgkmcnt(0)
	s_add_u32 s18, s4, 0x303400
	s_addc_u32 s19, s5, 0
	v_add_u32_e32 v5, 1, v0
	v_mul_lo_u32 v5, v5, v2
	global_load_dword v2, v1, s[18:19] sc1
	s_waitcnt vmcnt(0)
	v_cmp_lt_u32_e32 vcc, v2, v5
	s_and_saveexec_b64 s[14:15], vcc
	s_cbranch_execz .LBB0_151
	s_add_u32 s16, s4, 0x300200
	s_addc_u32 s17, s5, 0
	s_mov_b32 s9, 1
	s_mov_b64 s[22:23], 0
	s_branch .LBB0_142

.LBB0_144:
	global_load_dword v2, v1, s[18:19] sc1
	s_add_i32 s9, s9, 1
	s_mov_b64 s[28:29], -1
	s_waitcnt vmcnt(0)
	v_cmp_ge_u32_e32 vcc, v2, v5
	s_orn2_b64 s[26:27], vcc, exec
	s_branch .LBB0_141

.LBB0_155:
	s_or_b64 exec, exec, s[14:15]
	v_cvt_f32_u32_e32 v4, v2
	s_waitcnt vmcnt(0)
	v_readfirstlane_b32 s9, v3
	s_add_u32 s12, s4, 0x303400
	s_addc_u32 s13, s5, 0
	v_rcp_iflag_f32_e32 v4, v4
	v_add_u32_e32 v0, s9, v0
	v_add_u32_e32 v5, 1, v0
	s_mov_b64 s[16:17], 0
	v_mul_f32_e32 v3, 0x4f7ffffe, v4
	v_cvt_u32_f32_e32 v3, v3
	v_sub_u32_e32 v4, 0, v2
	v_mul_lo_u32 v4, v4, v3
	v_mul_hi_u32 v4, v3, v4
	v_add_u32_e32 v3, v3, v4
	v_mul_hi_u32 v3, v0, v3
	v_mul_lo_u32 v4, v3, v2
	v_sub_u32_e32 v0, v0, v4
	v_add_u32_e32 v6, 1, v3
	v_cmp_ge_u32_e32 vcc, v0, v2
	v_sub_u32_e32 v4, v0, v2
	s_nop 0
	v_cndmask_b32_e32 v3, v3, v6, vcc
	v_cndmask_b32_e32 v0, v0, v4, vcc
	v_add_u32_e32 v4, 1, v3
	v_cmp_ge_u32_e32 vcc, v0, v2
	s_nop 1
	v_cndmask_b32_e32 v0, v3, v4, vcc
	v_mul_lo_u32 v3, v2, v0
	v_add_u32_e32 v2, v3, v2
	v_cmp_ne_u32_e32 vcc, v5, v2
	v_mov_b32_e32 v5, v2
	v_mov_b64_e32 v[2:3], s[12:13]
	s_and_saveexec_b64 s[14:15], vcc
	s_cbranch_execz .LBB0_167
	global_load_dword v2, v1, s[12:13] sc1
	s_mov_b64 s[22:23], 0
	s_waitcnt vmcnt(0)
	v_cmp_lt_u32_e32 vcc, v2, v5
	s_and_saveexec_b64 s[18:19], vcc
	s_cbranch_execz .LBB0_166
	s_add_u32 s16, s4, 0x300200
	s_addc_u32 s17, s5, 0
	s_mov_b32 s9, 1
	s_mov_b64 s[4:5], 0
	s_branch .LBB0_159

.LBB0_161:
	global_load_dword v2, v1, s[12:13] sc1
	s_add_i32 s9, s9, 1
	s_mov_b64 s[26:27], -1
	s_waitcnt vmcnt(0)
	v_cmp_ge_u32_e32 vcc, v2, v5
	s_orn2_b64 s[24:25], vcc, exec
	s_branch .LBB0_158

.LBB0_262:
	s_or_b64 exec, exec, s[14:15]
	s_waitcnt vmcnt(0)
	v_readfirstlane_b32 s9, v3
	v_sub_u32_e32 v4, 0, v2
	s_add_u32 s12, s4, 0x303400
	v_add_u32_e32 v3, s9, v0
	v_cvt_f32_u32_e32 v0, v2
	s_addc_u32 s13, s5, 0
	s_mov_b64 s[16:17], 0
	v_rcp_iflag_f32_e32 v0, v0
	s_nop 0
	v_mul_f32_e32 v0, 0x4f7ffffe, v0
	v_cvt_u32_f32_e32 v0, v0
	v_mul_lo_u32 v4, v4, v0
	v_mul_hi_u32 v4, v0, v4
	v_add_u32_e32 v0, v0, v4
	v_mul_hi_u32 v0, v3, v0
	v_mul_lo_u32 v4, v0, v2
	v_sub_u32_e32 v4, v3, v4
	v_cmp_ge_u32_e32 vcc, v4, v2
	v_add_u32_e32 v5, 1, v0
	v_add_u32_e32 v3, 1, v3
	v_cndmask_b32_e32 v0, v0, v5, vcc
	v_sub_u32_e32 v5, v4, v2
	v_cndmask_b32_e32 v4, v4, v5, vcc
	v_cmp_ge_u32_e32 vcc, v4, v2
	v_add_u32_e32 v4, 1, v0
	s_nop 0
	v_cndmask_b32_e32 v0, v0, v4, vcc
	v_mul_lo_u32 v4, v2, v0
	v_add_u32_e32 v2, v4, v2
	v_cmp_ne_u32_e32 vcc, v3, v2
	v_mov_b32_e32 v5, v2
	v_mov_b64_e32 v[2:3], s[12:13]
	s_and_saveexec_b64 s[14:15], vcc
	s_cbranch_execz .LBB0_274
	global_load_dword v2, v1, s[12:13] sc1
	s_mov_b64 s[22:23], 0
	s_waitcnt vmcnt(0)
	v_cmp_lt_u32_e32 vcc, v2, v5
	s_and_saveexec_b64 s[18:19], vcc
	s_cbranch_execz .LBB0_273
	s_add_u32 s16, s4, 0x300200
	s_addc_u32 s17, s5, 0
	s_mov_b32 s9, 1
	s_mov_b64 s[4:5], 0
	s_branch .LBB0_266

.LBB0_802:
	s_or_b64 exec, exec, s[14:15]
	v_cvt_f32_u32_e32 v5, v3
	s_waitcnt vmcnt(0)
	v_readfirstlane_b32 s9, v4
	v_sub_u32_e32 v4, 0, v3
	v_rcp_iflag_f32_e32 v5, v5
	v_add_u32_e32 v6, s9, v0
	v_mul_f32_e32 v5, 0x4f7ffffe, v5
	v_cvt_u32_f32_e32 v5, v5
	v_mul_lo_u32 v0, v4, v5
	v_mul_hi_u32 v0, v5, v0
	v_add_u32_e32 v0, v5, v0
	v_mul_hi_u32 v0, v6, v0
	v_mul_lo_u32 v4, v0, v3
	v_sub_u32_e32 v4, v6, v4
	v_add_u32_e32 v5, 1, v0
	v_cmp_ge_u32_e32 vcc, v4, v3
	s_nop 1
	v_cndmask_b32_e32 v0, v0, v5, vcc
	v_sub_u32_e32 v5, v4, v3
	v_cndmask_b32_e32 v4, v4, v5, vcc
	v_add_u32_e32 v5, 1, v0
	v_cmp_ge_u32_e32 vcc, v4, v3
	v_add_u32_e32 v4, 1, v6
	s_nop 0
	v_cndmask_b32_e32 v0, v0, v5, vcc
	v_mul_lo_u32 v5, v3, v0
	v_add_u32_e32 v3, v5, v3
	v_cmp_ne_u32_e32 vcc, v4, v3
	s_and_saveexec_b64 s[12:13], vcc
	s_xor_b64 s[12:13], exec, s[12:13]
	s_cbranch_execz .LBB0_816
	s_waitcnt lgkmcnt(0)
	s_add_u32 s24, s4, 0x303400
	s_addc_u32 s25, s5, 0
	v_add_u32_e32 v5, 1, v0
	v_mul_lo_u32 v5, v5, v2
	global_load_dword v2, v1, s[24:25] sc1
	s_waitcnt vmcnt(0)
	v_cmp_lt_u32_e32 vcc, v2, v5
	s_and_saveexec_b64 s[14:15], vcc
	s_cbranch_execz .LBB0_815
	s_add_u32 s22, s4, 0x300200
	s_addc_u32 s23, s5, 0
	s_mov_b32 s9, 1
	s_mov_b64 s[26:27], 0
	s_branch .LBB0_806

.LBB0_808:
	global_load_dword v2, v1, s[24:25] sc1
	s_add_i32 s9, s9, 1
	s_mov_b64 s[38:39], -1
	s_waitcnt vmcnt(0)
	v_cmp_ge_u32_e32 vcc, v2, v5
	s_orn2_b64 s[36:37], vcc, exec
	s_branch .LBB0_805

.LBB0_819:
	s_or_b64 exec, exec, s[22:23]
	s_waitcnt vmcnt(0)
	v_readfirstlane_b32 s9, v3
	v_sub_u32_e32 v4, 0, v2
	s_add_u32 s14, s4, 0x303400
	v_add_u32_e32 v3, s9, v0
	v_cvt_f32_u32_e32 v0, v2
	s_addc_u32 s15, s5, 0
	s_mov_b64 s[24:25], 0
	v_rcp_iflag_f32_e32 v0, v0
	s_nop 0
	v_mul_f32_e32 v0, 0x4f7ffffe, v0
	v_cvt_u32_f32_e32 v0, v0
	v_mul_lo_u32 v4, v4, v0
	v_mul_hi_u32 v4, v0, v4
	v_add_u32_e32 v0, v0, v4
	v_mul_hi_u32 v0, v3, v0
	v_mul_lo_u32 v4, v0, v2
	v_sub_u32_e32 v4, v3, v4
	v_cmp_ge_u32_e32 vcc, v4, v2
	v_add_u32_e32 v5, 1, v0
	v_add_u32_e32 v3, 1, v3
	v_cndmask_b32_e32 v0, v0, v5, vcc
	v_sub_u32_e32 v5, v4, v2
	v_cndmask_b32_e32 v4, v4, v5, vcc
	v_cmp_ge_u32_e32 vcc, v4, v2
	v_add_u32_e32 v4, 1, v0
	s_nop 0
	v_cndmask_b32_e32 v0, v0, v4, vcc
	v_mul_lo_u32 v4, v2, v0
	v_add_u32_e32 v2, v4, v2
	v_cmp_ne_u32_e32 vcc, v3, v2
	v_mov_b32_e32 v5, v2
	v_mov_b64_e32 v[2:3], s[14:15]
	s_and_saveexec_b64 s[22:23], vcc
	s_cbranch_execz .LBB0_831
	global_load_dword v2, v1, s[14:15] sc1
	s_mov_b64 s[28:29], 0
	s_waitcnt vmcnt(0)
	v_cmp_lt_u32_e32 vcc, v2, v5
	s_and_saveexec_b64 s[26:27], vcc
	s_cbranch_execz .LBB0_830
	s_add_u32 s24, s4, 0x300200
	s_addc_u32 s25, s5, 0
	s_mov_b32 s9, 1
	s_mov_b64 s[4:5], 0
	s_branch .LBB0_823

.LBB0_825:
	global_load_dword v2, v1, s[14:15] sc1
	s_add_i32 s9, s9, 1
	s_mov_b64 s[38:39], -1
	s_waitcnt vmcnt(0)
	v_cmp_ge_u32_e32 vcc, v2, v5
	s_orn2_b64 s[36:37], vcc, exec
	s_branch .LBB0_822
